# NA key-row body specialised per half-wave: 12 always-out-of-window score registers and 2 of 8 PV MFMAs skipped
# speedup vs baseline: 1.0035x; 1.0035x over previous
; #define LAS __attribute__((address_space(3)))
;     ...
;         if (st < nst && ku >= rs && ku < rs + 8) {
;             f32x16 s0 = (f32x16){}, s1 = (f32x16){};
; #pragma unroll
;             for (int s4 = 0; s4 < 4; ++s4) {
;                 const bf16x8 a0 = KFRAG(Kt, kb0, kb1, 0, hh, s4), a1 = KFRAG(Kt, kb0, kb1, 1, hh, s4);
;                 s0 = __builtin_amdgcn_mfma_f32_32x32x16_bf16(a0, qf[s4], s0, 0, 0, 0);
;                 s1 = __builtin_amdgcn_mfma_f32_32x32x16_bf16(a1, qf[s4], s1, 0, 0, 0);
;             }
;             const LAS float* trow = tab + (ku - r + 7) * 31;
; #pragma unroll
;             for (int q = 0; q < 16; ++q) { const int ko = (q & 3) + 8 * (q >> 2);
;                 int i0 = ibase + ko, i1 = ibase + ko + 32; i0 = min(max(i0, 0), 30); i1 = min(max(i1, 0), 30);
;                 const float b0 = trow[i0], b1 = trow[i1];
;                 const float p0 = (float)((mlo >> (ko + 4 * hi)) & 1u), p1 = (float)((mhi >> (ko + 4 * hi)) & 1u);
;                 s0[q] = s0[q] + b0 + (p0 - 1.f) * 1e30f; s1[q] = s1[q] + b1 + (p1 - 1.f) * 1e30f; }
;             const float rm = rowmax32(s0, s1);
;             if (__any(rm > mrun + 8.f)) { const float mn = fmaxf(mrun, rm), f = __builtin_amdgcn_exp2f(mrun - mn); lrun *= f; mrun = mn; O[0] *= f; O[1] *= f; }
.LBB0_263:
	s_or_b32 s8, s29, s27
	s_add_i32 s9, s8, s1
	s_cmp_lt_i32 s8, s16
	s_cselect_b64 s[30:31], -1, 0
	s_cmp_ge_i32 s9, s18
	s_cselect_b64 s[34:35], -1, 0
	s_cmp_lt_i32 s9, s24
	s_cselect_b64 s[36:37], -1, 0
	s_and_b64 s[30:31], s[30:31], s[36:37]
	s_and_b64 s[30:31], s[30:31], s[34:35]
	s_andn2_b64 vcc, exec, s[30:31]
	s_cbranch_vccnz .LBB0_262
	s_lshl_b32 s8, s29, 15
	s_add_i32 s8, s28, s8
	s_add_i32 s8, s25, s8
	s_sub_i32 s9, s9, s0
	s_lshl_b32 s9, s9, 7
	s_add_i32 s9, s19, s9
	v_readfirstlane_b32 s30, v238
	s_nop 1
	s_bitcmp1_b32 s30, 6
	s_cbranch_scc1 .Lna_h1
	v_lshl_add_u32 v210, v106, 2, s9
	ds_read_b32 v210, v210 offset:896
	v_lshl_add_u32 v211, v110, 2, s9
	ds_read_b32 v211, v211 offset:896
	v_lshl_add_u32 v212, v114, 2, s9
	ds_read_b32 v212, v212 offset:896
	v_lshl_add_u32 v213, v118, 2, s9
	ds_read_b32 v213, v213 offset:896
	v_lshl_add_u32 v214, v122, 2, s9
	ds_read_b32 v214, v214 offset:896
	v_lshl_add_u32 v215, v126, 2, s9
	ds_read_b32 v215, v215 offset:896
	v_lshl_add_u32 v216, v130, 2, s9
	ds_read_b32 v216, v216 offset:896
	v_lshl_add_u32 v217, v134, 2, s9
	ds_read_b32 v217, v217 offset:896
	v_lshl_add_u32 v218, v138, 2, s9
	ds_read_b32 v218, v218 offset:896
	v_lshl_add_u32 v219, v142, 2, s9
	ds_read_b32 v219, v219 offset:896
	v_lshl_add_u32 v220, v146, 2, s9
	ds_read_b32 v220, v220 offset:896
	v_lshl_add_u32 v221, v150, 2, s9
	ds_read_b32 v221, v221 offset:896
	v_lshl_add_u32 v222, v154, 2, s9
	ds_read_b32 v222, v222 offset:896
	v_lshl_add_u32 v223, v158, 2, s9
	ds_read_b32 v223, v223 offset:896
	v_lshl_add_u32 v224, v162, 2, s9
	ds_read_b32 v224, v224 offset:896
	v_lshl_add_u32 v225, v166, 2, s9
	ds_read_b32 v225, v225 offset:896
	v_lshl_add_u32 v172, v107, 2, s9
	ds_read_b32 v172, v172 offset:896
	v_lshl_add_u32 v173, v111, 2, s9
	ds_read_b32 v173, v173 offset:896
	v_lshl_add_u32 v174, v115, 2, s9
	ds_read_b32 v174, v174 offset:896
	v_lshl_add_u32 v175, v119, 2, s9
	ds_read_b32 v175, v175 offset:896
	v_add_u32_e32 v192, s8, v102
	v_add_u32_e32 v193, s8, v105
	ds_read_b128 v[226:229], v192
	ds_read_b128 v[230:233], v192 offset:8192
	ds_read_b128 v[234:237], v193
	ds_read_b128 v[188:191], v193 offset:8192
	ds_read_b128 v[2:5], v192 offset:512
	ds_read_b128 v[6:9], v192 offset:8704
	ds_read_b128 v[10:13], v193 offset:512
	s_waitcnt lgkmcnt(6)
	v_mfma_f32_32x32x16_bf16 v[48:63], v[226:229], v[80:83], v[210:225]
	ds_read_b128 v[226:229], v193 offset:8704
	s_waitcnt lgkmcnt(6)
	v_mfma_f32_32x32x16_bf16 v[64:79], v[230:233], v[80:83], v[172:187]
	s_waitcnt lgkmcnt(5)
	v_mfma_f32_32x32x16_bf16 v[48:63], v[234:237], v[84:87], v[48:63]
	s_waitcnt lgkmcnt(4)
	v_mfma_f32_32x32x16_bf16 v[64:79], v[188:191], v[84:87], v[64:79]
	s_waitcnt lgkmcnt(3)
	v_mfma_f32_32x32x16_bf16 v[48:63], v[2:5], v[88:91], v[48:63]
	s_waitcnt lgkmcnt(2)
	v_mfma_f32_32x32x16_bf16 v[64:79], v[6:9], v[88:91], v[64:79]
	s_waitcnt lgkmcnt(1)
	v_mfma_f32_32x32x16_bf16 v[48:63], v[10:13], v[92:95], v[48:63]
	s_waitcnt lgkmcnt(0)
	v_mfma_f32_32x32x16_bf16 v[64:79], v[226:229], v[92:95], v[64:79]
	v_add_u32_e32 v192, s8, v103
	v_add_u32_e32 v193, s8, v104
	ds_read_b64_tr_b16 v[226:227], v192 offset:16384
	ds_read_b64_tr_b16 v[228:229], v193 offset:18432
	ds_read_b64_tr_b16 v[230:231], v192 offset:16896
	ds_read_b64_tr_b16 v[232:233], v193 offset:18944
	ds_read_b64_tr_b16 v[234:235], v192 offset:20480
	ds_read_b64_tr_b16 v[236:237], v193 offset:22528
	ds_read_b64_tr_b16 v[188:189], v192 offset:20992
	ds_read_b64_tr_b16 v[190:191], v193 offset:23040
	s_nop 2
	v_max_f32_e32 v214, v48, v49
	v_max_f32_e32 v215, v50, v51
	v_max3_f32 v214, v214, v52, v53
	v_max3_f32 v215, v215, v54, v55
	v_max3_f32 v214, v214, v56, v57
	v_max3_f32 v215, v215, v58, v59
	v_max3_f32 v214, v214, v60, v61
	v_max3_f32 v215, v215, v62, v63
	v_max3_f32 v214, v214, v64, v65
	v_max3_f32 v215, v215, v66, v67
	v_max_f32_e32 v214, v214, v215
	v_mov_b32_e32 v215, v214
	s_nop 1
	v_permlane32_swap_b32_e32 v214, v215
	v_max_f32_e32 v214, v214, v215
	v_add_f32_e32 v215, 0x41000000, v171
	v_cmp_gt_f32_e32 vcc, v214, v215
	s_cbranch_vccz .Lna_keep_ref_h0
	v_max_f32_e32 v215, v171, v214
	v_sub_f32_e32 v216, v171, v215
	v_exp_f32_e32 v216, v216
	v_mov_b32_e32 v171, v215
	v_mul_f32_e32 v167, v167, v216
	v_pk_mul_f32 v[46:47], v[46:47], v[216:217] op_sel_hi:[1,0]
	v_pk_mul_f32 v[44:45], v[44:45], v[216:217] op_sel_hi:[1,0]
	v_pk_mul_f32 v[42:43], v[42:43], v[216:217] op_sel_hi:[1,0]
	v_pk_mul_f32 v[40:41], v[40:41], v[216:217] op_sel_hi:[1,0]
	v_pk_mul_f32 v[38:39], v[38:39], v[216:217] op_sel_hi:[1,0]
	v_pk_mul_f32 v[36:37], v[36:37], v[216:217] op_sel_hi:[1,0]
	v_pk_mul_f32 v[34:35], v[34:35], v[216:217] op_sel_hi:[1,0]
	v_pk_mul_f32 v[32:33], v[32:33], v[216:217] op_sel_hi:[1,0]
	v_pk_mul_f32 v[30:31], v[30:31], v[216:217] op_sel_hi:[1,0]
	v_pk_mul_f32 v[28:29], v[28:29], v[216:217] op_sel_hi:[1,0]
	v_pk_mul_f32 v[26:27], v[26:27], v[216:217] op_sel_hi:[1,0]
	v_pk_mul_f32 v[24:25], v[24:25], v[216:217] op_sel_hi:[1,0]
	v_pk_mul_f32 v[22:23], v[22:23], v[216:217] op_sel_hi:[1,0]
	v_pk_mul_f32 v[20:21], v[20:21], v[216:217] op_sel_hi:[1,0]
	v_pk_mul_f32 v[18:19], v[18:19], v[216:217] op_sel_hi:[1,0]
	v_pk_mul_f32 v[16:17], v[16:17], v[216:217] op_sel_hi:[1,0]
; #define LAS __attribute__((address_space(3)))
; __device__ __forceinline__ unsigned cvtpk(float lo, float hi) { f32x2 v = {lo, hi}; bf16x2_t b = __builtin_convertvector(v, bf16x2_t); return __builtin_bit_cast(unsigned, b); }
; __device__ __forceinline__ float exp_pack(f32x16& s0, f32x16& s1, float mm, bf16x8* P) {
;     float sum0 = 0.f, sum1 = 0.f;
; #pragma unroll
;     for (int r = 0; r < 16; ++r) { s0[r] = __builtin_amdgcn_exp2f(s0[r] - mm); s1[r] = __builtin_amdgcn_exp2f(s1[r] - mm); sum0 += s0[r]; sum1 += s1[r]; }
; #pragma unroll
;     for (int sp = 0; sp < 2; ++sp) {
;         u32x4 w0, w1;
;         w0.x = cvtpk(s0[8 * sp + 0], s0[8 * sp + 1]); w0.y = cvtpk(s0[8 * sp + 2], s0[8 * sp + 3]); w0.z = cvtpk(s0[8 * sp + 4], s0[8 * sp + 5]); w0.w = cvtpk(s0[8 * sp + 6], s0[8 * sp + 7]);
;         w1.x = cvtpk(s1[8 * sp + 0], s1[8 * sp + 1]); w1.y = cvtpk(s1[8 * sp + 2], s1[8 * sp + 3]); w1.z = cvtpk(s1[8 * sp + 4], s1[8 * sp + 5]); w1.w = cvtpk(s1[8 * sp + 6], s1[8 * sp + 7]);
;         P[sp] = __builtin_bit_cast(bf16x8, w0); P[2 + sp] = __builtin_bit_cast(bf16x8, w1);
;     }
;     return sum0 + sum1;
; }
;     ...
;         if (st < nst && ku >= rs && ku < rs + 8) {
;             f32x16 s0 = (f32x16){}, s1 = (f32x16){};
; #pragma unroll
;             for (int s4 = 0; s4 < 4; ++s4) {
;                 const bf16x8 a0 = KFRAG(Kt, kb0, kb1, 0, hh, s4), a1 = KFRAG(Kt, kb0, kb1, 1, hh, s4);
;                 s0 = __builtin_amdgcn_mfma_f32_32x32x16_bf16(a0, qf[s4], s0, 0, 0, 0);
;                 s1 = __builtin_amdgcn_mfma_f32_32x32x16_bf16(a1, qf[s4], s1, 0, 0, 0);
;             }
;             const LAS float* trow = tab + (ku - r + 7) * 31;
; #pragma unroll
;             for (int q = 0; q < 16; ++q) { const int ko = (q & 3) + 8 * (q >> 2);
;                 int i0 = ibase + ko, i1 = ibase + ko + 32; i0 = min(max(i0, 0), 30); i1 = min(max(i1, 0), 30);
;                 const float b0 = trow[i0], b1 = trow[i1];
;                 const float p0 = (float)((mlo >> (ko + 4 * hi)) & 1u), p1 = (float)((mhi >> (ko + 4 * hi)) & 1u);
;                 s0[q] = s0[q] + b0 + (p0 - 1.f) * 1e30f; s1[q] = s1[q] + b1 + (p1 - 1.f) * 1e30f; }
;             const float rm = rowmax32(s0, s1);
;             if (__any(rm > mrun + 8.f)) { const float mn = fmaxf(mrun, rm), f = __builtin_amdgcn_exp2f(mrun - mn); lrun *= f; mrun = mn; O[0] *= f; O[1] *= f; }
.Lna_keep_ref_h0:
	v_sub_f32_e32 v48, v48, v171
	v_exp_f32_e32 v48, v48
	v_sub_f32_e32 v49, v49, v171
	v_exp_f32_e32 v49, v49
	v_sub_f32_e32 v50, v50, v171
	v_exp_f32_e32 v50, v50
	v_sub_f32_e32 v51, v51, v171
	v_exp_f32_e32 v51, v51
	v_sub_f32_e32 v52, v52, v171
	v_exp_f32_e32 v52, v52
	v_sub_f32_e32 v53, v53, v171
	v_exp_f32_e32 v53, v53
	v_sub_f32_e32 v54, v54, v171
	v_exp_f32_e32 v54, v54
	v_sub_f32_e32 v55, v55, v171
	v_exp_f32_e32 v55, v55
	v_sub_f32_e32 v56, v56, v171
	v_exp_f32_e32 v56, v56
	v_sub_f32_e32 v57, v57, v171
	v_exp_f32_e32 v57, v57
	v_sub_f32_e32 v58, v58, v171
	v_exp_f32_e32 v58, v58
	v_sub_f32_e32 v59, v59, v171
	v_exp_f32_e32 v59, v59
	v_sub_f32_e32 v60, v60, v171
	v_exp_f32_e32 v60, v60
	v_sub_f32_e32 v61, v61, v171
	v_exp_f32_e32 v61, v61
	v_sub_f32_e32 v62, v62, v171
	v_exp_f32_e32 v62, v62
	v_sub_f32_e32 v63, v63, v171
	v_exp_f32_e32 v63, v63
	v_sub_f32_e32 v64, v64, v171
	v_exp_f32_e32 v64, v64
	v_sub_f32_e32 v65, v65, v171
	v_exp_f32_e32 v65, v65
	v_sub_f32_e32 v66, v66, v171
	v_exp_f32_e32 v66, v66
	v_sub_f32_e32 v67, v67, v171
	v_exp_f32_e32 v67, v67
	v_cvt_pk_bf16_f32 v2, v48, v49
	v_cvt_pk_bf16_f32 v3, v50, v51
	v_cvt_pk_bf16_f32 v4, v52, v53
	v_cvt_pk_bf16_f32 v5, v54, v55
	v_cvt_pk_bf16_f32 v6, v56, v57
	v_cvt_pk_bf16_f32 v7, v58, v59
	v_cvt_pk_bf16_f32 v8, v60, v61
	v_cvt_pk_bf16_f32 v9, v62, v63
	s_waitcnt lgkmcnt(6)
	v_mfma_f32_32x32x16_bf16 v[32:47], v[226:229], v[2:5], v[32:47]
	ds_read_b64_tr_b16 v[226:227], v192 offset:24576
	ds_read_b64_tr_b16 v[228:229], v193 offset:26624
	v_cvt_pk_bf16_f32 v10, v64, v65
	v_cvt_pk_bf16_f32 v11, v66, v67
	v_mov_b32_e32 v12, 0
	v_mov_b32_e32 v13, 0
	s_waitcnt lgkmcnt(6)
	v_mfma_f32_32x32x16_bf16 v[16:31], v[230:233], v[2:5], v[16:31]
	ds_read_b64_tr_b16 v[230:231], v192 offset:25088
	ds_read_b64_tr_b16 v[232:233], v193 offset:27136
	v_add_f32_e32 v214, v48, v49
	v_add_f32_e32 v215, v64, v65
	v_add_f32_e32 v214, v50, v214
	v_add_f32_e32 v215, v66, v215
	v_add_f32_e32 v214, v51, v214
	s_waitcnt lgkmcnt(6)
	v_mfma_f32_32x32x16_bf16 v[32:47], v[234:237], v[6:9], v[32:47]
	v_add_f32_e32 v215, v67, v215
	v_add_f32_e32 v214, v52, v214
	v_add_f32_e32 v214, v53, v214
	v_add_f32_e32 v214, v54, v214
	v_add_f32_e32 v214, v55, v214
	s_waitcnt lgkmcnt(4)
	v_mfma_f32_32x32x16_bf16 v[16:31], v[188:191], v[6:9], v[16:31]
	v_add_f32_e32 v214, v56, v214
	v_add_f32_e32 v214, v57, v214
	v_add_f32_e32 v214, v58, v214
	v_add_f32_e32 v214, v59, v214
	v_add_f32_e32 v214, v60, v214
	s_waitcnt lgkmcnt(2)
	v_mfma_f32_32x32x16_bf16 v[32:47], v[226:229], v[10:13], v[32:47]
	v_add_f32_e32 v214, v61, v214
	v_add_f32_e32 v214, v62, v214
	v_add_f32_e32 v214, v63, v214
	s_waitcnt lgkmcnt(0)
	v_mfma_f32_32x32x16_bf16 v[16:31], v[230:233], v[10:13], v[16:31]
	v_add_f32_e32 v214, v214, v215
	v_add_f32_e32 v167, v167, v214
	s_branch .LBB0_262
.Lna_h1:
	v_lshl_add_u32 v222, v154, 2, s9
	ds_read_b32 v222, v222 offset:896
	v_lshl_add_u32 v223, v158, 2, s9
	ds_read_b32 v223, v223 offset:896
	v_lshl_add_u32 v224, v162, 2, s9
	ds_read_b32 v224, v224 offset:896
	v_lshl_add_u32 v225, v166, 2, s9
	ds_read_b32 v225, v225 offset:896
	v_lshl_add_u32 v172, v107, 2, s9
	ds_read_b32 v172, v172 offset:896
	v_lshl_add_u32 v173, v111, 2, s9
	ds_read_b32 v173, v173 offset:896
	v_lshl_add_u32 v174, v115, 2, s9
	ds_read_b32 v174, v174 offset:896
	v_lshl_add_u32 v175, v119, 2, s9
	ds_read_b32 v175, v175 offset:896
	v_lshl_add_u32 v176, v123, 2, s9
	ds_read_b32 v176, v176 offset:896
	v_lshl_add_u32 v177, v127, 2, s9
	ds_read_b32 v177, v177 offset:896
	v_lshl_add_u32 v178, v131, 2, s9
	ds_read_b32 v178, v178 offset:896
	v_lshl_add_u32 v179, v135, 2, s9
	ds_read_b32 v179, v179 offset:896
	v_lshl_add_u32 v180, v139, 2, s9
	ds_read_b32 v180, v180 offset:896
	v_lshl_add_u32 v181, v143, 2, s9
	ds_read_b32 v181, v181 offset:896
	v_lshl_add_u32 v182, v147, 2, s9
	ds_read_b32 v182, v182 offset:896
	v_lshl_add_u32 v183, v151, 2, s9
	ds_read_b32 v183, v183 offset:896
	v_lshl_add_u32 v184, v155, 2, s9
	ds_read_b32 v184, v184 offset:896
	v_lshl_add_u32 v185, v159, 2, s9
	ds_read_b32 v185, v185 offset:896
	v_lshl_add_u32 v186, v163, 2, s9
	ds_read_b32 v186, v186 offset:896
	v_lshl_add_u32 v187, v168, 2, s9
	ds_read_b32 v187, v187 offset:896
	v_add_u32_e32 v192, s8, v102
	v_add_u32_e32 v193, s8, v105
	ds_read_b128 v[226:229], v192
	ds_read_b128 v[230:233], v192 offset:8192
	ds_read_b128 v[234:237], v193
	ds_read_b128 v[188:191], v193 offset:8192
	ds_read_b128 v[2:5], v192 offset:512
	ds_read_b128 v[6:9], v192 offset:8704
	ds_read_b128 v[10:13], v193 offset:512
	s_waitcnt lgkmcnt(6)
	v_mfma_f32_32x32x16_bf16 v[48:63], v[226:229], v[80:83], v[210:225]
	ds_read_b128 v[226:229], v193 offset:8704
	s_waitcnt lgkmcnt(6)
	v_mfma_f32_32x32x16_bf16 v[64:79], v[230:233], v[80:83], v[172:187]
	s_waitcnt lgkmcnt(5)
	v_mfma_f32_32x32x16_bf16 v[48:63], v[234:237], v[84:87], v[48:63]
	s_waitcnt lgkmcnt(4)
	v_mfma_f32_32x32x16_bf16 v[64:79], v[188:191], v[84:87], v[64:79]
	s_waitcnt lgkmcnt(3)
	v_mfma_f32_32x32x16_bf16 v[48:63], v[2:5], v[88:91], v[48:63]
	s_waitcnt lgkmcnt(2)
	v_mfma_f32_32x32x16_bf16 v[64:79], v[6:9], v[88:91], v[64:79]
	s_waitcnt lgkmcnt(1)
	v_mfma_f32_32x32x16_bf16 v[48:63], v[10:13], v[92:95], v[48:63]
	s_waitcnt lgkmcnt(0)
	v_mfma_f32_32x32x16_bf16 v[64:79], v[226:229], v[92:95], v[64:79]
	v_add_u32_e32 v192, s8, v103
	v_add_u32_e32 v193, s8, v104
	ds_read_b64_tr_b16 v[226:227], v192 offset:20480
	ds_read_b64_tr_b16 v[228:229], v193 offset:22528
	ds_read_b64_tr_b16 v[230:231], v192 offset:20992
	ds_read_b64_tr_b16 v[232:233], v193 offset:23040
	ds_read_b64_tr_b16 v[234:235], v192 offset:24576
	ds_read_b64_tr_b16 v[236:237], v193 offset:26624
	ds_read_b64_tr_b16 v[188:189], v192 offset:25088
	ds_read_b64_tr_b16 v[190:191], v193 offset:27136
	s_nop 2
	v_max_f32_e32 v214, v60, v61
	v_max_f32_e32 v215, v62, v63
	v_max3_f32 v214, v214, v64, v65
	v_max3_f32 v215, v215, v66, v67
	v_max3_f32 v214, v214, v68, v69
	v_max3_f32 v215, v215, v70, v71
	v_max3_f32 v214, v214, v72, v73
	v_max3_f32 v215, v215, v74, v75
	v_max3_f32 v214, v214, v76, v77
	v_max3_f32 v215, v215, v78, v79
	v_max_f32_e32 v214, v214, v215
	v_mov_b32_e32 v215, v214
	s_nop 1
	v_permlane32_swap_b32_e32 v214, v215
	v_max_f32_e32 v214, v214, v215
	v_add_f32_e32 v215, 0x41000000, v171
	v_cmp_gt_f32_e32 vcc, v214, v215
	s_cbranch_vccz .Lna_keep_ref_h1
; __device__ __forceinline__ unsigned cvtpk(float lo, float hi) { f32x2 v = {lo, hi}; bf16x2_t b = __builtin_convertvector(v, bf16x2_t); return __builtin_bit_cast(unsigned, b); }
; __device__ __forceinline__ float exp_pack(f32x16& s0, f32x16& s1, float mm, bf16x8* P) {
;     float sum0 = 0.f, sum1 = 0.f;
; #pragma unroll
;     for (int r = 0; r < 16; ++r) { s0[r] = __builtin_amdgcn_exp2f(s0[r] - mm); s1[r] = __builtin_amdgcn_exp2f(s1[r] - mm); sum0 += s0[r]; sum1 += s1[r]; }
; #pragma unroll
;     for (int sp = 0; sp < 2; ++sp) {
;         u32x4 w0, w1;
;         w0.x = cvtpk(s0[8 * sp + 0], s0[8 * sp + 1]); w0.y = cvtpk(s0[8 * sp + 2], s0[8 * sp + 3]); w0.z = cvtpk(s0[8 * sp + 4], s0[8 * sp + 5]); w0.w = cvtpk(s0[8 * sp + 6], s0[8 * sp + 7]);
;         w1.x = cvtpk(s1[8 * sp + 0], s1[8 * sp + 1]); w1.y = cvtpk(s1[8 * sp + 2], s1[8 * sp + 3]); w1.z = cvtpk(s1[8 * sp + 4], s1[8 * sp + 5]); w1.w = cvtpk(s1[8 * sp + 6], s1[8 * sp + 7]);
;         P[sp] = __builtin_bit_cast(bf16x8, w0); P[2 + sp] = __builtin_bit_cast(bf16x8, w1);
;     }
;     return sum0 + sum1;
; }
;     ...
;             if (__any(rm > mrun + 8.f)) { const float mn = fmaxf(mrun, rm), f = __builtin_amdgcn_exp2f(mrun - mn); lrun *= f; mrun = mn; O[0] *= f; O[1] *= f; }
;             bf16x8 P[4];
;             lrun += exp_pack(s0, s1, mrun, P);
; #pragma unroll
;             for (int ks = 0; ks < 4; ++ks)
; #pragma unroll
;                 for (int e = 0; e < 2; ++e) { const bf16x8 vf = vfrag(Vt, vb0, vb1, ks, 2 * hh + e); O[e] = __builtin_amdgcn_mfma_f32_32x32x16_bf16(vf, P[ks], O[e], 0, 0, 0); }
	v_max_f32_e32 v215, v171, v214
	v_sub_f32_e32 v216, v171, v215
	v_exp_f32_e32 v216, v216
	v_mov_b32_e32 v171, v215
	v_mul_f32_e32 v167, v167, v216
	v_pk_mul_f32 v[46:47], v[46:47], v[216:217] op_sel_hi:[1,0]
	v_pk_mul_f32 v[44:45], v[44:45], v[216:217] op_sel_hi:[1,0]
	v_pk_mul_f32 v[42:43], v[42:43], v[216:217] op_sel_hi:[1,0]
	v_pk_mul_f32 v[40:41], v[40:41], v[216:217] op_sel_hi:[1,0]
	v_pk_mul_f32 v[38:39], v[38:39], v[216:217] op_sel_hi:[1,0]
	v_pk_mul_f32 v[36:37], v[36:37], v[216:217] op_sel_hi:[1,0]
	v_pk_mul_f32 v[34:35], v[34:35], v[216:217] op_sel_hi:[1,0]
	v_pk_mul_f32 v[32:33], v[32:33], v[216:217] op_sel_hi:[1,0]
	v_pk_mul_f32 v[30:31], v[30:31], v[216:217] op_sel_hi:[1,0]
	v_pk_mul_f32 v[28:29], v[28:29], v[216:217] op_sel_hi:[1,0]
	v_pk_mul_f32 v[26:27], v[26:27], v[216:217] op_sel_hi:[1,0]
	v_pk_mul_f32 v[24:25], v[24:25], v[216:217] op_sel_hi:[1,0]
	v_pk_mul_f32 v[22:23], v[22:23], v[216:217] op_sel_hi:[1,0]
	v_pk_mul_f32 v[20:21], v[20:21], v[216:217] op_sel_hi:[1,0]
	v_pk_mul_f32 v[18:19], v[18:19], v[216:217] op_sel_hi:[1,0]
	v_pk_mul_f32 v[16:17], v[16:17], v[216:217] op_sel_hi:[1,0]
.Lna_keep_ref_h1:
	v_sub_f32_e32 v60, v60, v171
	v_exp_f32_e32 v60, v60
	v_sub_f32_e32 v61, v61, v171
	v_exp_f32_e32 v61, v61
	v_sub_f32_e32 v62, v62, v171
	v_exp_f32_e32 v62, v62
	v_sub_f32_e32 v63, v63, v171
	v_exp_f32_e32 v63, v63
	v_sub_f32_e32 v64, v64, v171
	v_exp_f32_e32 v64, v64
	v_sub_f32_e32 v65, v65, v171
	v_exp_f32_e32 v65, v65
	v_sub_f32_e32 v66, v66, v171
	v_exp_f32_e32 v66, v66
	v_sub_f32_e32 v67, v67, v171
	v_exp_f32_e32 v67, v67
	v_sub_f32_e32 v68, v68, v171
	v_exp_f32_e32 v68, v68
	v_sub_f32_e32 v69, v69, v171
	v_exp_f32_e32 v69, v69
	v_sub_f32_e32 v70, v70, v171
	v_exp_f32_e32 v70, v70
	v_sub_f32_e32 v71, v71, v171
	v_exp_f32_e32 v71, v71
	v_sub_f32_e32 v72, v72, v171
	v_exp_f32_e32 v72, v72
	v_sub_f32_e32 v73, v73, v171
	v_exp_f32_e32 v73, v73
	v_sub_f32_e32 v74, v74, v171
	v_exp_f32_e32 v74, v74
	v_sub_f32_e32 v75, v75, v171
	v_exp_f32_e32 v75, v75
	v_sub_f32_e32 v76, v76, v171
	v_exp_f32_e32 v76, v76
	v_sub_f32_e32 v77, v77, v171
	v_exp_f32_e32 v77, v77
	v_sub_f32_e32 v78, v78, v171
	v_exp_f32_e32 v78, v78
	v_sub_f32_e32 v79, v79, v171
	v_exp_f32_e32 v79, v79
	v_mov_b32_e32 v6, 0
	v_mov_b32_e32 v7, 0
	v_cvt_pk_bf16_f32 v8, v60, v61
	v_cvt_pk_bf16_f32 v9, v62, v63
	v_cvt_pk_bf16_f32 v10, v64, v65
	v_cvt_pk_bf16_f32 v11, v66, v67
	v_cvt_pk_bf16_f32 v12, v68, v69
	v_cvt_pk_bf16_f32 v13, v70, v71
	s_waitcnt lgkmcnt(6)
	v_mfma_f32_32x32x16_bf16 v[32:47], v[226:229], v[6:9], v[32:47]
	ds_read_b64_tr_b16 v[226:227], v192 offset:28672
	ds_read_b64_tr_b16 v[228:229], v193 offset:30720
	v_cvt_pk_bf16_f32 v210, v72, v73
	v_cvt_pk_bf16_f32 v211, v74, v75
	v_cvt_pk_bf16_f32 v212, v76, v77
	v_cvt_pk_bf16_f32 v213, v78, v79
	s_waitcnt lgkmcnt(6)
	v_mfma_f32_32x32x16_bf16 v[16:31], v[230:233], v[6:9], v[16:31]
	ds_read_b64_tr_b16 v[230:231], v192 offset:29184
	ds_read_b64_tr_b16 v[232:233], v193 offset:31232
	v_add_f32_e32 v214, v60, v61
	v_add_f32_e32 v215, v64, v65
	v_add_f32_e32 v214, v62, v214
	v_add_f32_e32 v215, v66, v215
	v_add_f32_e32 v214, v63, v214
	s_waitcnt lgkmcnt(6)
	v_mfma_f32_32x32x16_bf16 v[32:47], v[234:237], v[10:13], v[32:47]
	v_add_f32_e32 v215, v67, v215
	v_add_f32_e32 v215, v68, v215
	v_add_f32_e32 v215, v69, v215
	v_add_f32_e32 v215, v70, v215
	v_add_f32_e32 v215, v71, v215
	s_waitcnt lgkmcnt(4)
	v_mfma_f32_32x32x16_bf16 v[16:31], v[188:191], v[10:13], v[16:31]
	v_add_f32_e32 v215, v72, v215
	v_add_f32_e32 v215, v73, v215
	v_add_f32_e32 v215, v74, v215
	v_add_f32_e32 v215, v75, v215
	v_add_f32_e32 v215, v76, v215
	s_waitcnt lgkmcnt(2)
	v_mfma_f32_32x32x16_bf16 v[32:47], v[226:229], v[210:213], v[32:47]
	v_add_f32_e32 v215, v77, v215
	v_add_f32_e32 v215, v78, v215
	v_add_f32_e32 v215, v79, v215
	s_waitcnt lgkmcnt(0)
	v_mfma_f32_32x32x16_bf16 v[16:31], v[230:233], v[210:213], v[16:31]
	v_add_f32_e32 v214, v214, v215
	v_add_f32_e32 v167, v167, v214
	s_branch .LBB0_262
